# attention unit prologues: full vmcnt(0) at unit start removed (it only waited for the previous unit's stores / the lam scalars)
# baseline (speedup 1.0000x reference)
; #define LAS __attribute__((address_space(3)))
; #define otid() ((wv << 6) | olane())
; template <int DK, int DV, int VAR>
; __device__ __forceinline__ void attn_pass(LAS unsigned char* lds, const bf16_t* Qg, const bf16_t* Kg, const bf16_t* Vg, int ntiles, float cs, f32x16 (&O)[DV / 32], float& lsum, int wv) {
;     constexpr int KP = DK * 2 + 16, KCH = DK / 8, NKC = 64 * KCH;
;     const int tid = otid(), lane = tid & 63, wid = tid >> 6, l32 = lane & 31, hf = lane >> 5;
;     bf16x8 qf[DK / 16];
;     { const bf16_t* qrow = Qg + (size_t)(wid * 32 + l32) * DK + hf * 8;
; #pragma unroll
;       for (int kk = 0; kk < DK / 16; ++kk) qf[kk] = *(const bf16x8*)(qrow + kk * 16); }
;     const int kc0 = tid, kc1 = tid + 512;
;     const int kr0 = kc0 / KCH, kq0 = kc0 % KCH, kr1 = kc1 / KCH, kq1 = kc1 % KCH;
;     const bool k1on = (kc1 < NKC);
;     const int kp = (DV == 128 ? (wid >> 2) : ((wid >> 1) & 1)) * 16 + (lane & 15);
;     const int vch = (DV == 128 ? (wid & 3) : (wid & 1)) * 4 + (lane >> 4);
;     const bool von = (DV == 128) || (wid < 4);
;     const bf16_t* kg0 = Kg + kr0 * DK + kq0 * 8; const bf16_t* kg1 = Kg + kr1 * DK + kq1 * 8;
;     const bf16_t* vg0 = Vg + (size_t)(2 * kp) * DV + vch * 8;
;     const unsigned kl0 = kr0 * KP + kq0 * 16, kl1 = kr1 * KP + kq1 * 16, vl0 = ATT_VOFF + (vch * 8) * ATT_VP + kp * 4;
;     u32x4 ka0, ka1, va0, va1;
;     { unsigned z0 = 0u; asm volatile("" : "+v"(z0)); ka1 = (u32x4){z0, z0, z0, z0}; } va0 = ka1; va1 = ka1; ka0 = ka1;
; template <int VAR> __device__ __forceinline__ void attn_unit_b(LAS unsigned char* lds, KP p, int bh, int qb, int wv) {
;     unsigned char* ws = p->ws;
;     const int b = bh >> 3, h = bh & 7;
;     const int tid_ = otid(); const int lane = tid_ & 63, wid = tid_ >> 6, l32 = lane & 31, hf = lane >> 5;
;     const int ntiles = qb == 0 ? CTX / 64 : TK / 64;
;     const int q0 = qb == 0 ? 0 : CTX + (qb - 1) * 256;
;     const bf16_t* QB = (const bf16_t*)(ws + WS_QB); const bf16_t* KB = (const bf16_t*)(ws + WS_KB); const bf16_t* VB = (const bf16_t*)(ws + WS_VB);
;     const float cs = 0.10206207261596577f * 1.4426950408889634f;
;     f32x16 O[2]; float lsum;
;     attn_pass<96, 64, VAR>(lds, QB + ((size_t)bh * TK + q0) * 96, KB + (size_t)bh * TK * 96, VB + (size_t)bh * TK * 64, ntiles, cs, O, lsum, wv);
.LBB0_824:
	s_cmpk_gt_i32 s16, 0xff
	s_mov_b64 s[0:1], -1
	s_cbranch_scc0 .LBB0_947
	s_cmpk_gt_u32 s16, 0x2ff
	s_cbranch_scc0 .LBB0_912
	s_waitcnt lgkmcnt(0)
	s_load_dwordx2 s[8:9], s[6:7], 0xd8
	s_cmpk_gt_u32 s16, 0x31f
	s_cbranch_scc0 .LBB0_866
	s_add_i32 s10, s16, 0xfffffce0
	s_mul_i32 s2, s10, 0x6c000
	s_waitcnt lgkmcnt(0)
	s_add_u32 s0, s8, s2
	s_addc_u32 s1, s9, 0
	v_mbcnt_lo_u32_b32 v156, -1, 0
	v_mbcnt_hi_u32_b32 v156, -1, v156
	s_add_u32 s0, s0, 0x11000000
	v_mbcnt_lo_u32_b32 v7, -1, 0
	v_mbcnt_hi_u32_b32 v7, -1, v7
	s_addc_u32 s1, s1, 0
	v_or_b32_e32 v8, s67, v7
	v_ashrrev_i32_e32 v6, 6, v8
	v_and_b32_e32 v116, 31, v7
	v_bfe_u32 v36, v7, 5, 1
	v_lshl_or_b32 v2, v6, 5, v116
	v_mov_b64_e32 v[0:1], s[0:1]
	v_mad_i64_i32 v[0:1], s[0:1], v2, s69, v[0:1]
	v_lshlrev_b32_e32 v48, 4, v36
	v_mov_b32_e32 v49, v193
	v_lshl_add_u64 v[0:1], v[0:1], 0, v[48:49]
	s_mov_b32 s1, 0x2aaaaaab
	global_load_dwordx4 v[100:103], v[0:1], off
	global_load_dwordx4 v[96:99], v[0:1], off offset:32
	global_load_dwordx4 v[92:95], v[0:1], off offset:64
	global_load_dwordx4 v[88:91], v[0:1], off offset:96
	global_load_dwordx4 v[84:87], v[0:1], off offset:128
	global_load_dwordx4 v[80:83], v[0:1], off offset:160
	v_mul_hi_i32 v0, v8, s1
	s_mul_i32 s76, s10, 0x900
	v_lshrrev_b32_e32 v1, 31, v0
	v_ashrrev_i32_e32 v0, 1, v0
	s_mul_hi_u32 s3, s76, 0xc0
	s_add_u32 s2, s8, s2
	v_add_u32_e32 v5, v0, v1
	s_addc_u32 s3, s9, s3
	v_mul_lo_u32 v0, v5, 12
	s_movk_i32 s0, 0x60
	s_add_u32 s4, s2, 0x12b00000
	v_sub_u32_e32 v4, v8, v0
	v_mul_lo_u32 v0, v5, s0
	s_addc_u32 s5, s3, 0
	v_ashrrev_i32_e32 v1, 31, v0
	v_lshlrev_b32_e32 v2, 3, v4
	v_ashrrev_i32_e32 v3, 31, v2
	v_lshl_add_u64 v[0:1], v[0:1], 1, s[4:5]
	v_mov_b32_e32 v104, v193
	v_lshl_add_u64 v[78:79], v[2:3], 1, v[0:1]
	s_barrier
	global_load_dwordx4 v[0:3], v[78:79], off
	v_add_u32_e32 v10, 0x200, v8
	v_mul_hi_i32 v9, v10, s1
	v_lshrrev_b32_e32 v11, 31, v9
	v_ashrrev_i32_e32 v9, 1, v9
	v_add_u32_e32 v9, v9, v11
	v_mul_lo_u32 v11, v9, 12
	v_sub_u32_e32 v10, v10, v11
	v_mul_lo_u32 v12, v9, s0
	v_ashrrev_i32_e32 v13, 31, v12
	v_lshlrev_b32_e32 v14, 3, v10
	v_mov_b32_e32 v106, v104
	v_mov_b32_e32 v107, v104
	v_ashrrev_i32_e32 v15, 31, v14
	s_movk_i32 s0, 0x100
	v_lshl_add_u64 v[12:13], v[12:13], 1, s[4:5]
	v_mov_b32_e32 v105, v104
	v_mov_b64_e32 v[110:111], v[106:107]
	v_cmp_gt_i32_e64 s[2:3], s0, v8
	v_lshl_add_u64 v[140:141], v[14:15], 1, v[12:13]
	v_mov_b64_e32 v[108:109], v[104:105]
	s_and_saveexec_b64 s[0:1], s[2:3]
	s_cbranch_execz .LBB0_829
	global_load_dwordx4 v[108:111], v[140:141], off

; #define LAS __attribute__((address_space(3)))
; #define otid() ((wv << 6) | olane())
; template <int DK, int DV, int VAR>
; __device__ __forceinline__ void attn_pass(LAS unsigned char* lds, const bf16_t* Qg, const bf16_t* Kg, const bf16_t* Vg, int ntiles, float cs, f32x16 (&O)[DV / 32], float& lsum, int wv) {
;     constexpr int KP = DK * 2 + 16, KCH = DK / 8, NKC = 64 * KCH;
;     const int tid = otid(), lane = tid & 63, wid = tid >> 6, l32 = lane & 31, hf = lane >> 5;
;     bf16x8 qf[DK / 16];
;     { const bf16_t* qrow = Qg + (size_t)(wid * 32 + l32) * DK + hf * 8;
; #pragma unroll
;       for (int kk = 0; kk < DK / 16; ++kk) qf[kk] = *(const bf16x8*)(qrow + kk * 16); }
;     const int kc0 = tid, kc1 = tid + 512;
;     const int kr0 = kc0 / KCH, kq0 = kc0 % KCH, kr1 = kc1 / KCH, kq1 = kc1 % KCH;
;     const bool k1on = (kc1 < NKC);
;     const int kp = (DV == 128 ? (wid >> 2) : ((wid >> 1) & 1)) * 16 + (lane & 15);
;     const int vch = (DV == 128 ? (wid & 3) : (wid & 1)) * 4 + (lane >> 4);
;     const bool von = (DV == 128) || (wid < 4);
;     const bf16_t* kg0 = Kg + kr0 * DK + kq0 * 8; const bf16_t* kg1 = Kg + kr1 * DK + kq1 * 8;
;     const bf16_t* vg0 = Vg + (size_t)(2 * kp) * DV + vch * 8;
;     const unsigned kl0 = kr0 * KP + kq0 * 16, kl1 = kr1 * KP + kq1 * 16, vl0 = ATT_VOFF + (vch * 8) * ATT_VP + kp * 4;
;     u32x4 ka0, ka1, va0, va1;
; template <int VAR> __device__ __forceinline__ void attn_unit_a(LAS unsigned char* lds, KP p, int l, int bh, int qb, int wv) {
;     unsigned char* ws = p->ws;
;     const int b = bh >> 2, h = bh & 3;
;     const int tid_ = otid(); const int lane = tid_ & 63, wid = tid_ >> 6, l32 = lane & 31, hf = lane >> 5;
;     const int ntiles = qb == 0 ? CTX / 64 : TK / 64;
;     const int q0 = qb == 0 ? 0 : CTX + (qb - 1) * 256;
;     const bf16_t* QA = (const bf16_t*)(ws + WS_QA); const bf16_t* KA = (const bf16_t*)(ws + WS_KA); const bf16_t* VA = (const bf16_t*)(ws + WS_VA);
;     const float cs = 0.125f * 1.4426950408889634f;
;     const float lam = ((const float*)(ws + WS_LAM))[l];
;     const float lam_init = ((const float*)(ws + WS_LAM))[8 + l];
;     f32x16 O[4]; float lsum;
;     const bf16_t* Vg = VA + (size_t)(b * 4 + h) * TK * 128;
;     attn_pass<64, 128, VAR>(lds, QA + ((size_t)(b * 8 + h * 2 + 0) * TK + q0) * 64, KA + (size_t)(b * 8 + h * 2 + 0) * TK * 64, Vg, ntiles, cs, O, lsum, wv);
.LBB0_866:
	s_and_b64 vcc, exec, s[0:1]
	s_cbranch_vccz .LBB0_988
	s_add_i32 s4, s16, 0xfffffd00
	s_lshr_b32 s11, s4, 2
	s_and_b32 s10, s16, 3
	s_waitcnt lgkmcnt(0)
	s_add_u32 s19, s8, 0x8400000
	s_addc_u32 s20, s9, 0
	s_add_u32 s17, s8, 0x9600000
	s_addc_u32 s18, s9, 0
	s_lshl_b64 s[0:1], s[90:91], 2
	s_add_u32 s0, s8, s0
	s_addc_u32 s1, s9, s1
	s_add_u32 s2, s0, 0x3100000
	v_mov_b32_e32 v0, 0x3100000
	v_mbcnt_lo_u32_b32 v180, -1, 0
	v_mbcnt_hi_u32_b32 v180, -1, v180
	s_addc_u32 s3, s1, 0
	global_load_dword v182, v0, s[0:1]
	global_load_dword v181, v193, s[2:3] offset:32
	s_lshl_b32 s0, s11, 3
	s_lshl_b32 s1, s10, 1
	v_mbcnt_lo_u32_b32 v4, -1, 0
	v_mbcnt_hi_u32_b32 v4, -1, v4
	s_or_b32 s21, s0, s1
	v_or_b32_e32 v5, s67, v4
	v_ashrrev_i32_e32 v6, 6, v5
	v_and_b32_e32 v32, 31, v4
	s_mul_i32 s0, s21, 0x48000
	v_lshl_or_b32 v0, v6, 5, v32
	s_mul_hi_u32 s1, s21, 0x48000
	s_add_u32 s2, s19, s0
	v_ashrrev_i32_e32 v1, 31, v0
	s_addc_u32 s3, s20, s1
	v_bfe_u32 v33, v4, 5, 1
	v_lshlrev_b64 v[0:1], 7, v[0:1]
	v_lshl_add_u64 v[0:1], s[2:3], 0, v[0:1]
	v_lshlrev_b32_e32 v80, 4, v33
	v_mov_b32_e32 v81, v193
	v_lshl_add_u64 v[0:1], v[0:1], 0, v[80:81]
	global_load_dwordx4 v[124:127], v[0:1], off
	global_load_dwordx4 v[120:123], v[0:1], off offset:32
	global_load_dwordx4 v[116:119], v[0:1], off offset:64
	global_load_dwordx4 v[112:115], v[0:1], off offset:96
	v_ashrrev_i32_e32 v1, 31, v5
	v_lshrrev_b32_e32 v1, 29, v1
	v_add_u32_e32 v1, v5, v1
	v_add_u32_e32 v0, 0x200, v5
	v_ashrrev_i32_e32 v13, 3, v1
	v_and_b32_e32 v1, -8, v1
	v_sub_u32_e32 v12, v5, v1
	v_ashrrev_i32_e32 v1, 31, v0
	v_lshrrev_b32_e32 v1, 29, v1
	v_add_u32_e32 v1, v0, v1
	v_ashrrev_i32_e32 v14, 3, v1
	v_and_b32_e32 v1, -8, v1
	s_add_u32 s0, s17, s0
	v_sub_u32_e32 v15, v0, v1
	v_lshlrev_b32_e32 v0, 6, v13
	s_addc_u32 s1, s18, s1
	v_ashrrev_i32_e32 v1, 31, v0
	v_lshlrev_b32_e32 v2, 3, v12
	v_ashrrev_i32_e32 v3, 31, v2
	v_lshl_add_u64 v[0:1], v[0:1], 1, s[0:1]
	v_mov_b32_e32 v128, v193
	v_lshl_add_u64 v[166:167], v[2:3], 1, v[0:1]
	s_barrier
	global_load_dwordx4 v[0:3], v[166:167], off
	v_lshlrev_b32_e32 v8, 6, v14
	v_ashrrev_i32_e32 v9, 31, v8
	v_lshlrev_b32_e32 v10, 3, v15
	v_ashrrev_i32_e32 v11, 31, v10
	v_lshl_add_u64 v[8:9], v[8:9], 1, s[0:1]
	v_cmp_gt_i32_e64 s[2:3], 0, v5
	v_lshl_add_u64 v[110:111], v[10:11], 1, v[8:9]
	v_mov_b32_e32 v129, v128
	v_mov_b32_e32 v130, v128
	v_mov_b32_e32 v131, v128
	s_and_saveexec_b64 s[0:1], s[2:3]
	s_cbranch_execz .LBB0_869
	global_load_dwordx4 v[128:131], v[110:111], off

; #define LAS __attribute__((address_space(3)))
; #define otid() ((wv << 6) | olane())
; template <int VAR> __device__ __forceinline__ void attn_unit_b(LAS unsigned char* lds, KP p, int bh, int qb, int wv) {
;     unsigned char* ws = p->ws;
;     const int b = bh >> 3, h = bh & 7;
;     const int tid_ = otid(); const int lane = tid_ & 63, wid = tid_ >> 6, l32 = lane & 31, hf = lane >> 5;
;     const int ntiles = qb == 0 ? CTX / 64 : TK / 64;
;     const int q0 = qb == 0 ? 0 : CTX + (qb - 1) * 256;
;     const bf16_t* QB = (const bf16_t*)(ws + WS_QB); const bf16_t* KB = (const bf16_t*)(ws + WS_KB); const bf16_t* VB = (const bf16_t*)(ws + WS_VB);
;     const float cs = 0.10206207261596577f * 1.4426950408889634f;
;     f32x16 O[2]; float lsum;
;     attn_pass<96, 64, VAR>(lds, QB + ((size_t)bh * TK + q0) * 96, KB + (size_t)bh * TK * 96, VB + (size_t)bh * TK * 64, ntiles, cs, O, lsum, wv);
; template <int VAR> __device__ __forceinline__ void attn_phase(LAS unsigned char* lds, KP p, int l, int wv) {
;     ...
;         else if (u < 768) { const int u2 = u - 256, r = u2 >> 8, c2 = u2 & 255, xcd = c2 & 7, j = c2 >> 3; attn_unit_b<VAR>(lds, p, xcd * 8 + (j >> 3) * 2 + r, 1 + (j & 7), wv); }
.LBB0_913:
	s_lshl_b32 s1, s16, 3
	s_lshr_b32 s2, s16, 5
	s_add_i32 s0, s16, 0xffffff00
	s_and_b32 s1, s1, 56
	s_and_b32 s17, s2, 6
	s_lshr_b32 s0, s0, 8
	s_or_b32 s10, s1, s17
	s_add_i32 s10, s10, s0
	s_load_dwordx2 s[0:1], s[6:7], 0xd8
	s_lshl_b32 s2, s16, 5
	s_and_b32 s11, s2, 0x700
	s_mul_i32 s76, s10, 0x900
	s_add_i32 s2, s11, s76
	s_mulk_i32 s2, 0xc0
	s_add_i32 s2, s2, 0xc000
	s_waitcnt lgkmcnt(0)
	s_add_u32 s2, s0, s2
	s_addc_u32 s3, s1, 0
	v_mbcnt_lo_u32_b32 v180, -1, 0
	v_mbcnt_hi_u32_b32 v180, -1, v180
	s_add_u32 s2, s2, 0x11000000
	v_mbcnt_lo_u32_b32 v9, -1, 0
	v_mbcnt_hi_u32_b32 v9, -1, v9
	s_addc_u32 s3, s3, 0
	v_or_b32_e32 v88, s67, v9
	v_ashrrev_i32_e32 v8, 6, v88
	v_and_b32_e32 v32, 31, v9
	v_bfe_u32 v10, v9, 5, 1
	v_lshl_or_b32 v2, v8, 5, v32
	v_mov_b64_e32 v[0:1], s[2:3]
	v_mad_i64_i32 v[0:1], s[2:3], v2, s69, v[0:1]
	v_lshlrev_b32_e32 v168, 4, v10
	v_mov_b32_e32 v169, v193
	v_lshl_add_u64 v[0:1], v[0:1], 0, v[168:169]
	s_mov_b32 s3, 0x2aaaaaab
	global_load_dwordx4 v[116:119], v[0:1], off
	global_load_dwordx4 v[112:115], v[0:1], off offset:32
	global_load_dwordx4 v[108:111], v[0:1], off offset:64
	global_load_dwordx4 v[104:107], v[0:1], off offset:96
	global_load_dwordx4 v[100:103], v[0:1], off offset:128
	global_load_dwordx4 v[96:99], v[0:1], off offset:160
	v_mul_hi_i32 v0, v88, s3
	s_mul_i32 s4, s10, 0x6c000
	v_lshrrev_b32_e32 v1, 31, v0
	v_ashrrev_i32_e32 v0, 1, v0
	s_mul_hi_u32 s5, s76, 0xc0
	s_add_u32 s4, s0, s4
	v_add_u32_e32 v12, v0, v1
	s_addc_u32 s5, s1, s5
	v_mul_lo_u32 v0, v12, 12
	s_movk_i32 s2, 0x60
	s_add_u32 s4, s4, 0x12b00000
	v_sub_u32_e32 v11, v88, v0
	v_mul_lo_u32 v76, v12, s2
	s_addc_u32 s5, s5, 0
	v_ashrrev_i32_e32 v77, 31, v76
	v_lshlrev_b32_e32 v78, 3, v11
	v_ashrrev_i32_e32 v79, 31, v78
	v_lshl_add_u64 v[0:1], v[76:77], 1, s[4:5]
	v_mov_b32_e32 v120, v193
	v_lshl_add_u64 v[4:5], v[78:79], 1, v[0:1]
	s_barrier
	global_load_dwordx4 v[0:3], v[4:5], off
	v_add_u32_e32 v6, 0x200, v88
	v_mul_hi_i32 v7, v6, s3
	v_lshrrev_b32_e32 v13, 31, v7
	v_ashrrev_i32_e32 v7, 1, v7
	v_add_u32_e32 v13, v7, v13
	v_mul_lo_u32 v7, v13, 12
	v_sub_u32_e32 v14, v6, v7
	v_mul_lo_u32 v80, v13, s2
	v_ashrrev_i32_e32 v81, 31, v80
	v_lshlrev_b32_e32 v82, 3, v14
	v_mov_b32_e32 v122, v120
	v_mov_b32_e32 v123, v120
	v_ashrrev_i32_e32 v83, 31, v82
	s_movk_i32 s2, 0x100
	v_lshl_add_u64 v[6:7], v[80:81], 1, s[4:5]
	v_mov_b32_e32 v121, v120
	v_mov_b64_e32 v[126:127], v[122:123]
	v_cmp_gt_i32_e64 s[2:3], s2, v88
	v_lshl_add_u64 v[6:7], v[82:83], 1, v[6:7]
	v_mov_b64_e32 v[124:125], v[120:121]
	s_and_saveexec_b64 s[4:5], s[2:3]
	s_cbranch_execz .LBB0_915
	global_load_dwordx4 v[124:127], v[6:7], off

; #define LAS __attribute__((address_space(3)))
; #define otid() ((wv << 6) | olane())
; template <int VAR> __device__ __forceinline__ void attn_unit_a(LAS unsigned char* lds, KP p, int l, int bh, int qb, int wv) {
;     unsigned char* ws = p->ws;
;     const int b = bh >> 2, h = bh & 3;
;     const int tid_ = otid(); const int lane = tid_ & 63, wid = tid_ >> 6, l32 = lane & 31, hf = lane >> 5;
;     const int ntiles = qb == 0 ? CTX / 64 : TK / 64;
;     const int q0 = qb == 0 ? 0 : CTX + (qb - 1) * 256;
;     const bf16_t* QA = (const bf16_t*)(ws + WS_QA); const bf16_t* KA = (const bf16_t*)(ws + WS_KA); const bf16_t* VA = (const bf16_t*)(ws + WS_VA);
;     const float cs = 0.125f * 1.4426950408889634f;
;     const float lam = ((const float*)(ws + WS_LAM))[l];
;     const float lam_init = ((const float*)(ws + WS_LAM))[8 + l];
;     f32x16 O[4]; float lsum;
;     const bf16_t* Vg = VA + (size_t)(b * 4 + h) * TK * 128;
;     attn_pass<64, 128, VAR>(lds, QA + ((size_t)(b * 8 + h * 2 + 0) * TK + q0) * 64, KA + (size_t)(b * 8 + h * 2 + 0) * TK * 64, Vg, ntiles, cs, O, lsum, wv);
; template <int VAR> __device__ __forceinline__ void attn_phase(LAS unsigned char* lds, KP p, int l, int wv) {
;     ...
;         if (u < 256) { const int xcd = u & 7, j = u >> 3; attn_unit_a<VAR>(lds, p, l, xcd * 4 + (j >> 3), 1 + (j & 7), wv); }
.LBB0_947:
	s_andn2_b64 vcc, exec, s[0:1]
	s_cbranch_vccnz .LBB0_823
	s_load_dwordx2 s[4:5], s[6:7], 0xd8
	s_lshl_b32 s0, s16, 2
	s_waitcnt lgkmcnt(0)
	s_and_b32 s9, s0, 28
	s_ashr_i32 s8, s16, 6
	s_lshl_b32 s0, s16, 5
	s_add_i32 s9, s9, s8
	s_and_b32 s19, s0, 0x700
	s_ashr_i32 s18, s9, 2
	s_and_b32 s17, s8, 3
	s_add_i32 s26, s19, 0x100
	s_add_u32 s24, s4, 0x8400000
	s_addc_u32 s25, s5, 0
	s_add_u32 s22, s4, 0x9600000
	s_addc_u32 s23, s5, 0
	s_lshl_b64 s[0:1], s[90:91], 2
	s_add_u32 s0, s4, s0
	s_addc_u32 s1, s5, s1
	s_add_u32 s2, s0, 0x3100000
	s_addc_u32 s3, s1, 0
	s_lshl_b32 s20, s18, 3
	s_lshl_b32 s21, s17, 1
	v_mov_b32_e32 v0, 0x3100000
	s_or_b32 s27, s20, s21
	v_mbcnt_lo_u32_b32 v216, -1, 0
	v_mbcnt_hi_u32_b32 v216, -1, v216
	global_load_dword v218, v0, s[0:1]
	global_load_dword v217, v193, s[2:3] offset:32
	s_mul_i32 s0, s27, 0x900
	s_mul_hi_i32 s1, s27, 0x900
	s_add_u32 s0, s0, s26
	v_mbcnt_lo_u32_b32 v91, -1, 0
	v_mbcnt_hi_u32_b32 v91, -1, v91
	s_addc_u32 s1, s1, 0
	v_or_b32_e32 v90, s67, v91
	v_ashrrev_i32_e32 v4, 6, v90
	v_and_b32_e32 v73, 31, v91
	s_lshl_b64 s[0:1], s[0:1], 7
	v_lshl_or_b32 v0, v4, 5, v73
	s_add_u32 s2, s24, s0
	v_ashrrev_i32_e32 v1, 31, v0
	s_addc_u32 s3, s25, s1
	v_bfe_u32 v32, v91, 5, 1
	v_lshlrev_b64 v[0:1], 7, v[0:1]
	v_lshl_add_u64 v[0:1], s[2:3], 0, v[0:1]
	v_lshlrev_b32_e32 v204, 4, v32
	v_mov_b32_e32 v205, v193
	v_lshl_add_u64 v[0:1], v[0:1], 0, v[204:205]
	global_load_dwordx4 v[140:143], v[0:1], off
	global_load_dwordx4 v[136:139], v[0:1], off offset:32
	global_load_dwordx4 v[132:135], v[0:1], off offset:64
	global_load_dwordx4 v[128:131], v[0:1], off offset:96
	v_ashrrev_i32_e32 v1, 31, v90
	v_lshrrev_b32_e32 v1, 29, v1
	v_add_u32_e32 v1, v90, v1
	v_add_u32_e32 v0, 0x200, v90
	v_ashrrev_i32_e32 v19, 3, v1
	v_and_b32_e32 v1, -8, v1
	v_sub_u32_e32 v18, v90, v1
	v_ashrrev_i32_e32 v1, 31, v0
	v_lshrrev_b32_e32 v1, 29, v1
	s_mul_i32 s0, s27, 0x48000
	v_add_u32_e32 v1, v0, v1
	s_mul_hi_i32 s1, s27, 0x48000
	s_add_u32 s0, s22, s0
	v_ashrrev_i32_e32 v20, 3, v1
	v_and_b32_e32 v1, -8, v1
	v_lshlrev_b32_e32 v64, 6, v19
	s_addc_u32 s1, s23, s1
	v_sub_u32_e32 v21, v0, v1
	v_ashrrev_i32_e32 v65, 31, v64
	v_lshlrev_b32_e32 v66, 3, v18
	v_lshlrev_b32_e32 v68, 6, v20
	v_ashrrev_i32_e32 v67, 31, v66
	v_ashrrev_i32_e32 v69, 31, v68
	v_lshlrev_b32_e32 v70, 3, v21
	v_lshl_add_u64 v[0:1], v[64:65], 1, s[0:1]
	v_ashrrev_i32_e32 v71, 31, v70
	v_mov_b32_e32 v144, v193
	v_lshl_add_u64 v[2:3], v[68:69], 1, s[0:1]
	v_lshl_add_u64 v[14:15], v[66:67], 1, v[0:1]
	v_lshl_add_u64 v[12:13], v[70:71], 1, v[2:3]
	s_barrier
	global_load_dwordx4 v[0:3], v[14:15], off
	v_cmp_gt_i32_e64 s[2:3], 0, v90
	v_mov_b32_e32 v145, v144
	v_mov_b32_e32 v146, v144
	v_mov_b32_e32 v147, v144
	s_and_saveexec_b64 s[0:1], s[2:3]
	s_cbranch_execz .LBB0_950
	global_load_dwordx4 v[144:147], v[12:13], off
